# pad1: stack4 + code placement: two s_nop 0 pads (entry, P4 setup) so every hot loop head sits at the baseline byte phase (shift = 0 mod 8)
# baseline (speedup 1.0000x reference)
_Z9hymba_fwd4Args:
	s_mov_b32 s99, 0
	s_nop 0
	s_load_dwordx2 s[92:93], s[0:1], 0xb0
	s_load_dwordx4 s[84:87], s[0:1], 0xa0
	s_load_dword s3, s[0:1], 0xb8
	s_load_dwordx8 s[4:11], s[0:1], 0x80
	s_load_dwordx16 s[36:51], s[0:1], 0x0
	s_load_dwordx16 s[52:67], s[0:1], 0x40
	s_waitcnt lgkmcnt(0)
	v_writelane_b32 v247, s4, 0
	s_nop 1
	v_writelane_b32 v247, s5, 1
	v_writelane_b32 v247, s6, 2
	v_writelane_b32 v247, s7, 3
	v_writelane_b32 v247, s8, 4
	v_writelane_b32 v247, s9, 5
	v_writelane_b32 v247, s10, 6
	v_writelane_b32 v247, s11, 7
	s_add_u32 s4, s0, 0xb8
	s_addc_u32 s5, s1, 0
	v_writelane_b32 v247, s4, 8
	v_readfirstlane_b32 s6, v0
	s_nop 0
	v_writelane_b32 v247, s5, 9
	v_writelane_b32 v247, s3, 10
	s_and_b32 s3, s3, 7
	s_cmp_lg_u32 s3, 0
	v_writelane_b32 v247, s2, 11
	v_writelane_b32 v247, s2, 12
	s_cbranch_scc1 .LBB0_2
	s_load_dword s2, s[0:1], 0xb8
	v_readlane_b32 s5, v247, 11
	s_ashr_i32 s3, s5, 31
	s_lshr_b32 s3, s3, 29
	s_add_i32 s3, s5, s3
	s_and_b32 s4, s3, -8
	s_waitcnt lgkmcnt(0)
	s_ashr_i32 s2, s2, 3
	s_sub_i32 s4, s5, s4
	s_mul_i32 s2, s2, s4
	s_ashr_i32 s3, s3, 3
	s_add_i32 s2, s2, s3
	v_writelane_b32 v247, s2, 12

.LBB0_625:
	s_cbranch_execz .LBB0_592
	s_nop 0
	s_add_u32 s4, s66, 0xbf00
	s_addc_u32 s5, s67, 0
	s_add_u32 s25, s66, 0xb00000
	s_addc_u32 s27, s67, 0
	s_add_u32 s2, s66, 0x12000000
	s_addc_u32 s3, s67, 0
	s_add_u32 s0, s66, 0xec40080
	s_addc_u32 s1, s67, 0
	s_add_u32 s24, s66, 0xb00100
	s_addc_u32 s26, s67, 0
	s_add_i32 s29, 0, 0x20174
	v_mov_b32_e32 v129, 0
	s_movk_i32 s28, 0x100
	v_mov_b32_e32 v140, s29
	s_mov_b32 s48, 0x1fffe0
	s_mov_b64 s[6:7], 0x40000
	s_mov_b64 s[8:9], 0x80
	s_mov_b32 s49, 0x40000
	s_mov_b64 s[10:11], 0x48000
	s_mov_b32 s50, 0x48000
	s_mov_b64 s[12:13], 0x50000
	s_mov_b32 s51, 0x50000
	s_mov_b64 s[14:15], 0x58000
	s_mov_b32 s52, 0x58000
	v_mov_b32_e32 v141, 1
	s_mov_b32 s100, 0
	s_branch .LBB0_628
